# v14: v13 + first/last-tile window-mask blocks in attention B made branch-free with batched LUT prefetch
# speedup vs baseline: 1.0132x; 1.0079x over previous
; template <int MODE>
; __device__ __forceinline__ void attn_unit(const UnitArgs& A, char* lds, const int wave_) {
;     ...
;     { const bf16_t* Qw = A.Qb + (long)(qb * QBLK + r32) * NZ + half * 64 + hi * 8;
; #pragma unroll
;       for (int d0 = 0; d0 < 4; ++d0) qr[d0] = *reinterpret_cast<const bf16x8*>(Qw + d0 * 16); }
;     const int sr = tid >> 4, sc = (tid & 15) * 8, vst0 = v_st(sr, sc);
;     const int vbase = (int)(uintptr_t)V_lds + v_rd_base(lane) + (MODE == 0 ? 0 : half * 1024);
;     const int ldk = A.ldk; const unsigned ldoff = (unsigned)(sr * ldk + sc) * 2u;
;     struct { bf16x8 vs0, vs1; } sr_[1];
;     const unsigned kdoff = (unsigned)(sr * ldk + (((tid & 15) ^ (sr & 7)) * 8)) * 2u;
;     const unsigned kdst0 = (unsigned)__builtin_amdgcn_readfirstlane((int)((unsigned)(uintptr_t)K_lds + (unsigned)wid * 1024u));
;     ...
;     auto zone_of = [&](int t) -> int { const int k0 = 64 * t, qw0 = A.q0 + 32 * qb; return (k0 + 63 - qw0 <= -128) ? 0 : ((k0 - qw0 - 31 >= 128) ? 2 : 1); };
;     ...
;     auto post = [&](f32x16& p0, f32x16& p1, int t) {
;         SBAR();
;         if (MODE == 0) {
;             if (zone_of(t) == 1) { const int k0 = 64 * t, qw0 = A.q0 + 32 * qb;
;                 const float* b = lutA + A.h * LUTA_STRIDE + (k0 - qw0 - r32 + 4 * hi + 320);
; #pragma unroll
;                 for (int r = 0; r < 16; ++r) { const int c = (r & 3) + 8 * (r >> 2); p0[r] += b[c]; p1[r] += b[32 + c]; } }
;         } else if (MODE == 1) {
;             const int kr = A.tile0 + t, rq = A.q0 + (qb >> 1);
; __global__ void __launch_bounds__(NTHREADS, 2) hymba_fwd(Args args) {
;     ...
;                 if (u < 1024) { p = u & 1; blk = (u >> 1) & 63; seq = u >> 7; R = SP / GW; row0 = (size_t)seq * SP; }
;                 else { const int v = u - 1024; p = v & 1; blk = (v >> 1) & 15; seq = v >> 5; R = SS / GW; row0 = (size_t)MP + (size_t)seq * SS; }
;                 const int r0 = 2 * blk; int lo = r0 - 4; lo = lo < 0 ? 0 : lo; lo = lo > R - 8 ? R - 8 : lo; int hi2 = r0 + 1 - 4; hi2 = hi2 < 0 ? 0 : hi2; hi2 = hi2 > R - 8 ? R - 8 : hi2; hi2 += 7;
;                 U.q0 = r0; U.h = p; U.tile0 = lo; U.R = R; U.NT = ((hi2 - lo + 1) + 1) & ~1; U.ldk = NZ; U.mshift = mshB;
;                 U.Qb = Z + (row0 + 128 * blk) * NZ + 1536 + 128 * p; U.Kb = Z + row0 * NZ + 1792 + 128 * p; U.Vb = Z + row0 * NZ + 2048 + 128 * p; U.Ob = MIX + (row0 + 128 * blk) * DM + 512 + 128 * p;
.LBB0_354:
	s_lshl_b32 s6, s96, 1
	v_sub_u32_e64 v57, s6, 4 clamp
	s_add_i32 s7, s4, -8
	v_readfirstlane_b32 s1, v57
	s_and_b32 s35, s26, 1
	s_min_u32 s88, s1, s7
	s_lshl_b32 s1, s96, 7
	s_add_u32 s30, s2, s1
	s_addc_u32 s31, s3, 0
	s_mul_i32 s1, s31, 0x1400
	s_mul_hi_u32 s5, s30, 0x1400
	s_add_i32 s5, s5, s1
	s_mul_i32 s1, s30, 0x1400
	s_add_u32 s1, s37, s1
	s_addc_u32 s5, s38, s5
	s_lshl_b32 s10, s35, 8
	s_add_u32 s8, s1, s10
	s_mul_i32 s1, s3, 0x1400
	s_mul_hi_u32 s3, s2, 0x1400
	s_addc_u32 s9, s5, 0
	s_add_i32 s3, s3, s1
	s_mul_i32 s1, s2, 0x1400
	s_add_u32 s1, s37, s1
	s_addc_u32 s2, s38, s3
	s_add_u32 s33, s1, s10
	s_addc_u32 s92, s2, 0
	s_add_u32 s89, s33, 0x1000
	s_addc_u32 s2, s92, 0
	s_and_b32 s27, s0, 3
	v_and_b32_e32 v106, 31, v56
	s_lshl_b32 s1, s27, 5
	s_ashr_i32 s41, s34, 8
	v_or_b32_e32 v0, s1, v106
	v_mul_u32_u24_e32 v144, 0x1400, v0
	s_lshl_b32 s28, s41, 6
	v_bfe_u32 v107, v56, 5, 1
	v_lshl_add_u64 v[0:1], s[8:9], 0, v[144:145]
	s_ashr_i32 s29, s28, 31
	v_lshl_add_u64 v[2:3], s[28:29], 1, v[0:1]
	v_lshlrev_b32_e32 v0, 4, v107
	v_mov_b32_e32 v1, v145
	v_lshl_add_u64 v[2:3], v[2:3], 0, v[0:1]
	v_ashrrev_i32_e32 v1, 4, v56
	global_load_dwordx4 v[92:95], v[2:3], off offset:3072
	global_load_dwordx4 v[88:91], v[2:3], off offset:3104
	global_load_dwordx4 v[84:87], v[2:3], off offset:3136
	global_load_dwordx4 v[80:83], v[2:3], off offset:3168
	v_and_b32_e32 v3, 0xfffff0, v1
	v_lshlrev_b32_e32 v4, 1, v1
	s_lshl_b32 s70, s0, 10
	s_add_i32 s3, 0, 0x8000
	v_and_or_b32 v3, v4, 8, v3
	s_cmp_lg_u32 s3, -1
	v_lshrrev_b32_e32 v3, 1, v3
	v_bfe_u32 v5, v56, 2, 2
	v_writelane_b32 v255, s3, 30
	s_cselect_b32 s3, s3, 0
	s_add_i32 s71, s4, -1
	v_and_b32_e32 v2, 15, v56
	v_lshrrev_b32_e32 v4, 1, v1
	v_or_b32_e32 v3, v3, v5
	v_and_b32_e32 v5, 3, v1
	s_add_i32 s70, s70, s3
	s_min_u32 s3, s88, s71
	v_and_or_b32 v4, v4, 4, v5
	v_lshlrev_b32_e32 v5, 4, v2
	s_lshl_b32 s4, s3, 6
	s_mul_i32 s3, s3, 0x50000
	v_and_b32_e32 v6, 48, v5
	s_mul_hi_u32 s9, s4, 0x1400
	s_add_u32 s4, s33, s3
	v_lshl_or_b32 v4, v4, 6, v6
	s_addc_u32 s5, s92, s9
	v_lshl_or_b32 v14, v3, 9, v4
	v_mul_lo_u32 v3, v1, s63
	s_add_u32 s8, s89, s3
	v_or_b32_e32 v144, v3, v5
	s_addc_u32 s9, s2, s9
	v_lshl_add_u64 v[6:7], s[8:9], 0, v[144:145]
	v_bitop3_b32 v1, v1, v2, 7 bitop3:0x6c
	v_add_co_u32_e32 v6, vcc, s74, v6
	v_lshl_or_b32 v104, v1, 4, v3
	global_load_dwordx4 v[2:5], v144, s[8:9]
	v_addc_co_u32_e32 v7, vcc, 0, v7, vcc
	global_load_dwordx4 v[6:9], v[6:7], off
	v_mov_b32_e32 v105, v145
	v_lshl_add_u64 v[10:11], s[4:5], 0, v[104:105]
	s_mov_b64 s[10:11], 0xe00
	v_lshl_add_u64 v[12:13], v[10:11], 0, s[10:11]
	s_mov_b32 s3, m0
	s_mov_b32 m0, s70
	s_nop 0
	global_load_lds_dwordx4 v[12:13], off
	s_mov_b32 m0, s3
	s_mov_b64 s[12:13], 0x28e00
	s_add_i32 s3, s70, 0x2000
	v_lshl_add_u64 v[10:11], v[10:11], 0, s[12:13]
	s_mov_b32 s4, m0
	s_mov_b32 m0, s3
	s_nop 0
	global_load_lds_dwordx4 v[10:11], off
	s_mov_b32 m0, s4
	s_or_b32 s3, s88, 1
	s_min_u32 s3, s3, s71
	s_lshl_b32 s4, s3, 6
	s_mul_i32 s3, s3, 0x50000
	s_mul_hi_u32 s9, s4, 0x1400
	s_add_u32 s4, s33, s3
	s_addc_u32 s5, s92, s9
	s_add_u32 s8, s89, s3
	v_add_u32_e32 v158, 0, v14
	s_addc_u32 s9, s2, s9
	s_waitcnt vmcnt(0)
	v_lshl_or_b32 v71, s41, 7, v0
	v_lshlrev_b32_e32 v0, 4, v56
	s_add_i32 s3, s70, 0x4000
	v_lshlrev_b32_e32 v70, 8, v106
	v_and_b32_e32 v72, 0x70, v0
	v_xad_u32 v0, v71, v72, v70
	v_add_u32_e32 v113, 0, v0
	s_waitcnt vmcnt(1)
	ds_write_b128 v158, v[2:5]
	s_waitcnt vmcnt(0)
	ds_write_b128 v158, v[6:9] offset:8192
	v_lshl_add_u64 v[2:3], s[8:9], 0, v[144:145]
	v_add_co_u32_e32 v2, vcc, s74, v2
	global_load_dwordx4 v[48:51], v144, s[8:9]
	s_nop 0
	v_addc_co_u32_e32 v3, vcc, 0, v3, vcc
	global_load_dwordx4 v[52:55], v[2:3], off
	v_lshl_add_u64 v[2:3], s[4:5], 0, v[104:105]
	v_lshl_add_u64 v[4:5], v[2:3], 0, s[10:11]
	s_mov_b32 s4, m0
	s_mov_b32 m0, s3
	s_nop 0
	global_load_lds_dwordx4 v[4:5], off
	s_mov_b32 m0, s4
	v_or_b32_e32 v4, 32, v71
	v_xad_u32 v4, v4, v72, v70
	v_lshl_add_u64 v[2:3], v[2:3], 0, s[12:13]
	v_add_u32_e32 v114, 0, v4
	s_add_i32 s3, s70, 0x6000
	s_mov_b32 s4, m0
	s_mov_b32 m0, s3
	s_nop 0
	global_load_lds_dwordx4 v[2:3], off
	s_mov_b32 m0, s4
	s_waitcnt lgkmcnt(0)
	s_barrier
	ds_read_b128 v[0:3], v113 offset:32768
	ds_read_b128 v[58:61], v113 offset:40960
	ds_read_b128 v[62:65], v114 offset:32768
	ds_read_b128 v[66:69], v114 offset:40960
	v_readlane_b32 s8, v255, 10
	v_readlane_b32 s22, v255, 24
	v_readlane_b32 s23, v255, 25
	v_readlane_b32 s9, v255, 11
	v_readlane_b32 s10, v255, 12
	v_readlane_b32 s11, v255, 13
	v_readlane_b32 s12, v255, 14
	v_readlane_b32 s13, v255, 15
	v_readlane_b32 s14, v255, 16
	v_readlane_b32 s15, v255, 17
	v_readlane_b32 s16, v255, 18
	v_readlane_b32 s17, v255, 19
	v_readlane_b32 s18, v255, 20
	v_readlane_b32 s19, v255, 21
	v_readlane_b32 s20, v255, 22
	v_readlane_b32 s21, v255, 23
	v_mov_b64_e32 v[46:47], s[22:23]
	v_mov_b64_e32 v[42:43], s[18:19]
	v_mov_b64_e32 v[44:45], s[20:21]
	v_mov_b64_e32 v[40:41], s[16:17]
	v_mov_b64_e32 v[38:39], s[14:15]
	v_mov_b64_e32 v[36:37], s[12:13]
	v_mov_b64_e32 v[34:35], s[10:11]
	v_mov_b64_e32 v[32:33], s[8:9]
	s_waitcnt lgkmcnt(3)
	s_nop 0
	v_mfma_f32_32x32x16_bf16 v[16:31], v[0:3], v[92:95], v[32:47]
	s_waitcnt lgkmcnt(2)
	v_mfma_f32_32x32x16_bf16 v[0:15], v[58:61], v[92:95], v[32:47]
	s_nop 6
	v_or_b32_e32 v32, 64, v71
	v_xad_u32 v32, v32, v72, v70
	v_add_u32_e32 v115, 0, v32
	ds_read_b128 v[32:35], v115 offset:32768
	ds_read_b128 v[36:39], v115 offset:40960
	s_waitcnt lgkmcnt(3)
	v_mfma_f32_32x32x16_bf16 v[16:31], v[62:65], v[88:91], v[16:31]
	v_or_b32_e32 v40, 0x60, v71
	v_xad_u32 v40, v40, v72, v70
	v_add_u32_e32 v116, 0, v40
	ds_read_b128 v[40:43], v116 offset:32768
	ds_read_b128 v[44:47], v116 offset:40960
	s_waitcnt lgkmcnt(4)
; template <int MODE>
; __device__ __forceinline__ void attn_unit(const UnitArgs& A, char* lds, const int wave_) {
;     ...
;             const int kr = A.tile0 + t, rq = A.q0 + (qb >> 1);
;             int rs = rq - 4; rs = rs < 0 ? 0 : rs; rs = rs > A.R - 8 ? A.R - 8 : rs;
;             if (kr < rs || kr >= rs + 8) {
; #pragma unroll
;                 for (int r = 0; r < 16; ++r) { p0[r] = NEG; p1[r] = NEG; }
;             } else {
;                 const int c = 32 * (qb & 1) + r32; int cs = c - 8; cs = cs < 0 ? 0 : cs; cs = cs > 48 ? 48 : cs;
;                 const float* b = lutB + ((2 * A.h + half) * 15 + (kr - rq + 7)) * 128 + 64 + 4 * hi - c;
; #pragma unroll
;                 for (int r = 0; r < 16; ++r) { const int cc = (r & 3) + 8 * (r >> 2), j = 4 * hi + cc;
;                     p0[r] = ((unsigned)(j - cs) < 16u) ? p0[r] + b[cc] : NEG; p1[r] = ((unsigned)(j + 32 - cs) < 16u) ? p1[r] + b[32 + cc] : NEG; } }
	v_mfma_f32_32x32x16_bf16 v[0:15], v[66:69], v[88:91], v[0:15]
	s_waitcnt lgkmcnt(3)
	v_mfma_f32_32x32x16_bf16 v[16:31], v[32:35], v[84:87], v[16:31]
	s_waitcnt lgkmcnt(2)
	v_mfma_f32_32x32x16_bf16 v[0:15], v[36:39], v[84:87], v[0:15]
	s_waitcnt lgkmcnt(1)
	v_mfma_f32_32x32x16_bf16 v[16:31], v[40:43], v[80:83], v[16:31]
	s_waitcnt lgkmcnt(0)
	v_mfma_f32_32x32x16_bf16 v[0:15], v[44:47], v[80:83], v[0:15]
	s_bfe_u32 s0, s0, 0x10001
	s_or_b32 s10, s0, s6
	v_sub_u32_e64 v32, s10, 4 clamp
	v_mov_b32_e32 v73, 0xf149f2ca
	v_readfirstlane_b32 s3, v32
	s_min_u32 s3, s3, s7
	s_add_i32 s91, s3, 8
	s_cmp_lt_u32 s88, s91
	v_cmp_le_u32_e32 vcc, s3, v57
	s_cselect_b64 s[4:5], -1, 0
	s_and_b64 s[4:5], vcc, s[4:5]
	s_andn2_b64 vcc, exec, s[4:5]
	v_lshlrev_b32_e32 v108, 2, v107
	v_and_or_b32 v112, s1, 32, v106
	v_mov_b32_e32 v72, 0xf149f2ca
	v_mov_b32_e32 v70, 0xf149f2ca
	v_mov_b32_e32 v68, 0xf149f2ca
	v_mov_b32_e32 v66, 0xf149f2ca
	v_mov_b32_e32 v64, 0xf149f2ca
	v_mov_b32_e32 v62, 0xf149f2ca
	v_mov_b32_e32 v60, 0xf149f2ca
	v_mov_b32_e32 v58, 0xf149f2ca
	v_mov_b32_e32 v47, 0xf149f2ca
	v_mov_b32_e32 v45, 0xf149f2ca
	v_mov_b32_e32 v43, 0xf149f2ca
	v_mov_b32_e32 v39, 0xf149f2ca
	v_mov_b32_e32 v37, 0xf149f2ca
	v_mov_b32_e32 v35, 0xf149f2ca
	v_mov_b32_e32 v33, 0xf149f2ca
	v_mov_b32_e32 v71, 0xf149f2ca
	v_mov_b32_e32 v69, 0xf149f2ca
	v_mov_b32_e32 v67, 0xf149f2ca
	v_mov_b32_e32 v65, 0xf149f2ca
	v_mov_b32_e32 v63, 0xf149f2ca
	v_mov_b32_e32 v61, 0xf149f2ca
	v_mov_b32_e32 v59, 0xf149f2ca
	v_mov_b32_e32 v57, 0xf149f2ca
	v_mov_b32_e32 v46, 0xf149f2ca
	v_mov_b32_e32 v44, 0xf149f2ca
	v_mov_b32_e32 v42, 0xf149f2ca
	v_mov_b32_e32 v38, 0xf149f2ca
	v_mov_b32_e32 v36, 0xf149f2ca
	v_mov_b32_e32 v34, 0xf149f2ca
	v_mov_b32_e32 v32, 0xf149f2ca
	v_mov_b32_e32 v74, 0xf149f2ca
	s_cbranch_vccnz .LBB0_420
	s_lshl_b32 s1, s35, 1
	s_add_i32 s1, s41, s1
	s_mul_i32 s1, s1, 15
	s_add_i32 s1, s88, s1
	s_sub_i32 s1, s1, s10
	s_lshl_b32 s1, s1, 9
	s_add_i32 s1, s1, 0
	s_add_i32 s1, s1, 0x14e00
	v_med3_u32 v40, v112, 8, 56
	v_lshl_add_u32 v32, v107, 4, s1
	v_lshlrev_b32_e32 v33, 2, v112
	v_sub_u32_e32 v41, v32, v33
	v_sub_u32_e32 v32, v108, v40
	v_add_u32_e32 v32, 8, v32
	v_cmp_gt_u32_e32 vcc, 16, v32
	v_mov_b32_e32 v32, 0xf149f2ca
	v_mov_b32_e32 v33, 0xf149f2ca
	ds_read_b32 v246, v41 offset:256
	ds_read_b32 v247, v41 offset:384
	ds_read_b32 v248, v41 offset:260
	ds_read_b32 v249, v41 offset:388
	ds_read_b32 v250, v41 offset:264
	ds_read_b32 v251, v41 offset:392
	ds_read_b32 v252, v41 offset:268
	ds_read_b32 v253, v41 offset:396
	s_waitcnt lgkmcnt(0)
	s_and_saveexec_b64 s[4:5], vcc
	v_add_f32_e32 v33, v16, v246
	s_or_b64 exec, exec, s[4:5]
	v_or_b32_e32 v16, 40, v108
	v_sub_u32_e32 v16, v16, v40
	v_cmp_gt_u32_e32 vcc, 16, v16
	s_and_saveexec_b64 s[4:5], vcc
	v_add_f32_e32 v32, v0, v247
	s_or_b64 exec, exec, s[4:5]
	v_sub_u32_e32 v0, 8, v40
	v_add3_u32 v16, v0, v108, 1
	v_cmp_gt_u32_e32 vcc, 16, v16
	v_mov_b32_e32 v34, 0xf149f2ca
	v_mov_b32_e32 v35, 0xf149f2ca
	s_and_saveexec_b64 s[4:5], vcc
	v_add_f32_e32 v35, v17, v248
	s_or_b64 exec, exec, s[4:5]
	v_or_b32_e32 v16, 41, v108
	v_sub_u32_e32 v16, v16, v40
	v_cmp_gt_u32_e32 vcc, 16, v16
	s_and_saveexec_b64 s[4:5], vcc
	v_add_f32_e32 v34, v1, v249
	s_or_b64 exec, exec, s[4:5]
	v_add3_u32 v1, v0, v108, 2
	v_cmp_gt_u32_e32 vcc, 16, v1
	v_mov_b32_e32 v36, 0xf149f2ca
	v_mov_b32_e32 v37, 0xf149f2ca
	s_and_saveexec_b64 s[4:5], vcc
	v_add_f32_e32 v37, v18, v250
	s_or_b64 exec, exec, s[4:5]
	v_or_b32_e32 v1, 42, v108
	v_sub_u32_e32 v1, v1, v40
	v_cmp_gt_u32_e32 vcc, 16, v1
	s_and_saveexec_b64 s[4:5], vcc
	v_add_f32_e32 v36, v2, v251
	s_or_b64 exec, exec, s[4:5]
	v_add3_u32 v1, v0, v108, 3
	v_cmp_gt_u32_e32 vcc, 16, v1
	v_mov_b32_e32 v38, 0xf149f2ca
	v_mov_b32_e32 v39, 0xf149f2ca
	s_and_saveexec_b64 s[4:5], vcc
	v_add_f32_e32 v39, v19, v252
	s_or_b64 exec, exec, s[4:5]
	v_or_b32_e32 v1, 43, v108
	v_sub_u32_e32 v1, v1, v40
	v_cmp_gt_u32_e32 vcc, 16, v1
	s_and_saveexec_b64 s[4:5], vcc
	v_add_f32_e32 v38, v3, v253
	s_or_b64 exec, exec, s[4:5]
	v_add3_u32 v1, v0, v108, 8
	v_cmp_gt_u32_e32 vcc, 16, v1
	v_mov_b32_e32 v42, 0xf149f2ca
	v_mov_b32_e32 v43, 0xf149f2ca
	ds_read_b32 v246, v41 offset:288
	ds_read_b32 v247, v41 offset:416
	ds_read_b32 v248, v41 offset:292
	ds_read_b32 v249, v41 offset:420
	ds_read_b32 v250, v41 offset:296
	ds_read_b32 v251, v41 offset:424
	ds_read_b32 v252, v41 offset:300
	ds_read_b32 v253, v41 offset:428
	s_waitcnt lgkmcnt(0)
; template <int MODE>
; __device__ __forceinline__ void attn_unit(const UnitArgs& A, char* lds, const int wave_) {
;     ...
;             const int kr = A.tile0 + t, rq = A.q0 + (qb >> 1);
;             int rs = rq - 4; rs = rs < 0 ? 0 : rs; rs = rs > A.R - 8 ? A.R - 8 : rs;
;             if (kr < rs || kr >= rs + 8) {
; #pragma unroll
;                 for (int r = 0; r < 16; ++r) { p0[r] = NEG; p1[r] = NEG; }
;             } else {
;                 const int c = 32 * (qb & 1) + r32; int cs = c - 8; cs = cs < 0 ? 0 : cs; cs = cs > 48 ? 48 : cs;
;                 const float* b = lutB + ((2 * A.h + half) * 15 + (kr - rq + 7)) * 128 + 64 + 4 * hi - c;
; #pragma unroll
;                 for (int r = 0; r < 16; ++r) { const int cc = (r & 3) + 8 * (r >> 2), j = 4 * hi + cc;
;                     p0[r] = ((unsigned)(j - cs) < 16u) ? p0[r] + b[cc] : NEG; p1[r] = ((unsigned)(j + 32 - cs) < 16u) ? p1[r] + b[32 + cc] : NEG; } }
	s_and_saveexec_b64 s[4:5], vcc
	v_add_f32_e32 v43, v20, v246
	s_or_b64 exec, exec, s[4:5]
	v_or_b32_e32 v1, 48, v108
	v_sub_u32_e32 v1, v1, v40
	v_cmp_gt_u32_e32 vcc, 16, v1
	s_and_saveexec_b64 s[4:5], vcc
	v_add_f32_e32 v42, v4, v247
	s_or_b64 exec, exec, s[4:5]
	v_add3_u32 v1, v0, v108, 9
	v_cmp_gt_u32_e32 vcc, 16, v1
	v_mov_b32_e32 v44, 0xf149f2ca
	v_mov_b32_e32 v45, 0xf149f2ca
	s_and_saveexec_b64 s[4:5], vcc
	v_add_f32_e32 v45, v21, v248
	s_or_b64 exec, exec, s[4:5]
	v_or_b32_e32 v1, 49, v108
	v_sub_u32_e32 v1, v1, v40
	v_cmp_gt_u32_e32 vcc, 16, v1
	s_and_saveexec_b64 s[4:5], vcc
	v_add_f32_e32 v44, v5, v249
	s_or_b64 exec, exec, s[4:5]
	v_add3_u32 v1, v0, v108, 10
	v_cmp_gt_u32_e32 vcc, 16, v1
	v_mov_b32_e32 v46, 0xf149f2ca
	v_mov_b32_e32 v47, 0xf149f2ca
	s_and_saveexec_b64 s[4:5], vcc
	v_add_f32_e32 v47, v22, v250
	s_or_b64 exec, exec, s[4:5]
	v_or_b32_e32 v1, 50, v108
	v_sub_u32_e32 v1, v1, v40
	v_cmp_gt_u32_e32 vcc, 16, v1
	s_and_saveexec_b64 s[4:5], vcc
	v_add_f32_e32 v46, v6, v251
	s_or_b64 exec, exec, s[4:5]
	v_add3_u32 v1, v0, v108, 11
	v_cmp_gt_u32_e32 vcc, 16, v1
	v_mov_b32_e32 v57, 0xf149f2ca
	v_mov_b32_e32 v58, 0xf149f2ca
	s_and_saveexec_b64 s[4:5], vcc
	v_add_f32_e32 v58, v23, v252
	s_or_b64 exec, exec, s[4:5]
	v_or_b32_e32 v1, 51, v108
	v_sub_u32_e32 v1, v1, v40
	v_cmp_gt_u32_e32 vcc, 16, v1
	s_and_saveexec_b64 s[4:5], vcc
	v_add_f32_e32 v57, v7, v253
	s_or_b64 exec, exec, s[4:5]
	v_add3_u32 v1, v0, v108, 16
	v_cmp_gt_u32_e32 vcc, 16, v1
	v_mov_b32_e32 v59, 0xf149f2ca
	v_mov_b32_e32 v60, 0xf149f2ca
	ds_read_b32 v246, v41 offset:320
	ds_read_b32 v247, v41 offset:448
	ds_read_b32 v248, v41 offset:324
	ds_read_b32 v249, v41 offset:452
	ds_read_b32 v250, v41 offset:328
	ds_read_b32 v251, v41 offset:456
	ds_read_b32 v252, v41 offset:332
	ds_read_b32 v253, v41 offset:460
	s_waitcnt lgkmcnt(0)
	s_and_saveexec_b64 s[4:5], vcc
	v_add_f32_e32 v60, v24, v246
	s_or_b64 exec, exec, s[4:5]
	v_or_b32_e32 v1, 56, v108
	v_sub_u32_e32 v1, v1, v40
	v_cmp_gt_u32_e32 vcc, 16, v1
	s_and_saveexec_b64 s[4:5], vcc
	v_add_f32_e32 v59, v8, v247
	s_or_b64 exec, exec, s[4:5]
	v_add3_u32 v1, v0, v108, 17
	v_cmp_gt_u32_e32 vcc, 16, v1
	v_mov_b32_e32 v61, 0xf149f2ca
	v_mov_b32_e32 v62, 0xf149f2ca
	s_and_saveexec_b64 s[4:5], vcc
	v_add_f32_e32 v62, v25, v248
	s_or_b64 exec, exec, s[4:5]
	v_or_b32_e32 v1, 57, v108
	v_sub_u32_e32 v1, v1, v40
	v_cmp_gt_u32_e32 vcc, 16, v1
	s_and_saveexec_b64 s[4:5], vcc
	v_add_f32_e32 v61, v9, v249
	s_or_b64 exec, exec, s[4:5]
	v_add3_u32 v1, v0, v108, 18
	v_cmp_gt_u32_e32 vcc, 16, v1
	v_mov_b32_e32 v63, 0xf149f2ca
	v_mov_b32_e32 v64, 0xf149f2ca
	s_and_saveexec_b64 s[4:5], vcc
	v_add_f32_e32 v64, v26, v250
	s_or_b64 exec, exec, s[4:5]
	v_or_b32_e32 v1, 58, v108
	v_sub_u32_e32 v1, v1, v40
	v_cmp_gt_u32_e32 vcc, 16, v1
	s_and_saveexec_b64 s[4:5], vcc
	v_add_f32_e32 v63, v10, v251
	s_or_b64 exec, exec, s[4:5]
	v_add3_u32 v1, v0, v108, 19
	v_cmp_gt_u32_e32 vcc, 16, v1
	v_mov_b32_e32 v65, 0xf149f2ca
	v_mov_b32_e32 v66, 0xf149f2ca
	s_and_saveexec_b64 s[4:5], vcc
	v_add_f32_e32 v66, v27, v252
	s_or_b64 exec, exec, s[4:5]
	v_or_b32_e32 v1, 59, v108
	v_sub_u32_e32 v1, v1, v40
	v_cmp_gt_u32_e32 vcc, 16, v1
	s_and_saveexec_b64 s[4:5], vcc
	v_add_f32_e32 v65, v11, v253
	s_or_b64 exec, exec, s[4:5]
	v_add3_u32 v1, v0, v108, 24
	v_cmp_gt_u32_e32 vcc, 16, v1
	v_mov_b32_e32 v67, 0xf149f2ca
	v_mov_b32_e32 v68, 0xf149f2ca
	ds_read_b32 v246, v41 offset:352
	ds_read_b32 v247, v41 offset:480
	ds_read_b32 v248, v41 offset:356
	ds_read_b32 v249, v41 offset:484
	ds_read_b32 v250, v41 offset:360
	ds_read_b32 v251, v41 offset:488
	ds_read_b32 v252, v41 offset:364
	ds_read_b32 v253, v41 offset:492
	s_waitcnt lgkmcnt(0)
	s_and_saveexec_b64 s[4:5], vcc
	v_add_f32_e32 v68, v28, v246
	s_or_b64 exec, exec, s[4:5]
	v_or_b32_e32 v1, 64, v108
	v_sub_u32_e32 v1, v1, v40
	v_cmp_gt_u32_e32 vcc, 16, v1
	s_and_saveexec_b64 s[4:5], vcc
	v_add_f32_e32 v67, v12, v247
	s_or_b64 exec, exec, s[4:5]
	v_add3_u32 v1, v0, v108, 25
	v_cmp_gt_u32_e32 vcc, 16, v1
	v_mov_b32_e32 v69, 0xf149f2ca
	v_mov_b32_e32 v70, 0xf149f2ca
	s_and_saveexec_b64 s[4:5], vcc
	v_add_f32_e32 v70, v29, v248
	s_or_b64 exec, exec, s[4:5]
	v_or_b32_e32 v1, 0x41, v108
	v_sub_u32_e32 v1, v1, v40
	v_cmp_gt_u32_e32 vcc, 16, v1
	s_and_saveexec_b64 s[4:5], vcc
	v_add_f32_e32 v69, v13, v249
	s_or_b64 exec, exec, s[4:5]
	v_add3_u32 v1, v0, v108, 26
	v_cmp_gt_u32_e32 vcc, 16, v1
	v_mov_b32_e32 v71, 0xf149f2ca
	v_mov_b32_e32 v72, 0xf149f2ca
	s_and_saveexec_b64 s[4:5], vcc
	v_add_f32_e32 v72, v30, v250
	s_or_b64 exec, exec, s[4:5]
	v_or_b32_e32 v1, 0x42, v108
	v_sub_u32_e32 v1, v1, v40
	v_cmp_gt_u32_e32 vcc, 16, v1
	s_and_saveexec_b64 s[4:5], vcc
	v_add_f32_e32 v71, v14, v251
	s_or_b64 exec, exec, s[4:5]
	v_add3_u32 v0, v0, v108, 27
	v_cmp_gt_u32_e32 vcc, 16, v0
	v_mov_b32_e32 v74, 0xf149f2ca
	v_mov_b32_e32 v73, 0xf149f2ca
	s_and_saveexec_b64 s[4:5], vcc
	v_add_f32_e32 v73, v31, v252
	s_or_b64 exec, exec, s[4:5]
	v_or_b32_e32 v0, 0x43, v108
	v_sub_u32_e32 v0, v0, v40
	v_cmp_gt_u32_e32 vcc, 16, v0
	s_and_saveexec_b64 s[4:5], vcc
	v_add_f32_e32 v74, v15, v253
	s_or_b64 exec, exec, s[4:5]

; #define SBAR() __builtin_amdgcn_sched_barrier(0)
; #define QK(P0, P1, KS, t) do { float v_ = -A.mshift; if (MODE == 0) { const int z_ = zone_of(t); v_ += (z_ == 0 ? A.farL : (z_ == 2 ? A.farR : 0.f)); } \
;     qkt(P0, P1, KS, qr, v_, r32, hi, half); } while (0)
; __device__ __forceinline__ void finishSM(f32x16& p0, f32x16& p1, float& l_reg, bf16x8& pa0, bf16x8& pa1, bf16x8& pa2, bf16x8& pa3) {
;     float ps = 0;
; #pragma unroll
;     for (int r = 0; r < 16; ++r) ps += p0[r];
; #pragma unroll
;     for (int r = 0; r < 16; ++r) ps += p1[r];
;     l_reg += ps;
;     ...
;     PK4(p0, 0, pa0); PK4(p0, 8, pa1); PK4(p1, 0, pa2); PK4(p1, 8, pa3);
; template <int MODE>
; __device__ __forceinline__ void attn_unit(const UnitArgs& A, char* lds, const int wave_) {
;     ...
;     SBAR(); QK(pB0, pB1, K_lds + SHM_K, NT - 1);
;     finishSM(pA0, pA1, l_reg, pa0, pa1, pa2, pa3); SBAR();
;     post(pB0, pB1, NT - 1); PV(0, pB0, pB1);
.LBB0_558:
	v_readlane_b32 s80, v255, 0
	s_mov_b64 s[70:71], 0x28000
	s_mov_b32 s82, 0x3a800000
	v_readlane_b32 s81, v255, 1
	ds_read_b128 v[32:35], v113 offset:49152
	ds_read_b128 v[96:99], v113 offset:57344
	ds_read_b128 v[100:103], v114 offset:49152
	ds_read_b128 v[178:181], v114 offset:57344
	v_readlane_b32 s4, v255, 10
	v_readlane_b32 s18, v255, 24
	v_readlane_b32 s19, v255, 25
	v_readlane_b32 s5, v255, 11
	v_readlane_b32 s6, v255, 12
	v_readlane_b32 s7, v255, 13
	v_readlane_b32 s8, v255, 14
	v_readlane_b32 s9, v255, 15
	v_readlane_b32 s10, v255, 16
	v_readlane_b32 s11, v255, 17
	v_readlane_b32 s12, v255, 18
	v_readlane_b32 s13, v255, 19
	v_readlane_b32 s14, v255, 20
	v_readlane_b32 s15, v255, 21
	v_readlane_b32 s16, v255, 22
	v_readlane_b32 s17, v255, 23
	v_mov_b64_e32 v[78:79], s[18:19]
	v_mov_b64_e32 v[74:75], s[14:15]
	v_mov_b64_e32 v[76:77], s[16:17]
	v_mov_b64_e32 v[72:73], s[12:13]
	v_mov_b64_e32 v[70:71], s[10:11]
	v_mov_b64_e32 v[68:69], s[8:9]
	v_mov_b64_e32 v[66:67], s[6:7]
	v_mov_b64_e32 v[64:65], s[4:5]
	s_waitcnt lgkmcnt(3)
	s_nop 0
	v_mfma_f32_32x32x16_bf16 v[48:63], v[32:35], v[92:95], v[64:79]
	s_waitcnt lgkmcnt(2)
	v_mfma_f32_32x32x16_bf16 v[32:47], v[96:99], v[92:95], v[64:79]
	s_nop 6
	ds_read_b128 v[64:67], v115 offset:49152
	ds_read_b128 v[68:71], v115 offset:57344
	s_waitcnt lgkmcnt(3)
	v_mfma_f32_32x32x16_bf16 v[48:63], v[100:103], v[88:91], v[48:63]
	ds_read_b128 v[72:75], v116 offset:49152
	ds_read_b128 v[76:79], v116 offset:57344
	s_waitcnt lgkmcnt(4)
	v_mfma_f32_32x32x16_bf16 v[32:47], v[178:181], v[88:91], v[32:47]
	s_waitcnt lgkmcnt(3)
	v_mfma_f32_32x32x16_bf16 v[48:63], v[64:67], v[84:87], v[48:63]
	v_cvt_pk_bf16_f32 v64, v117, v118
	v_cvt_pk_bf16_f32 v65, v119, v120
	v_cvt_pk_bf16_f32 v66, v121, v122
	v_cvt_pk_bf16_f32 v67, v123, v124
	s_nop 0
	v_permlane32_swap_b32_e32 v64, v66
	v_permlane32_swap_b32_e32 v65, v67
	s_waitcnt lgkmcnt(2)
	v_mfma_f32_32x32x16_bf16 v[32:47], v[68:71], v[84:87], v[32:47]
	v_cvt_pk_bf16_f32 v68, v125, v126
	v_cvt_pk_bf16_f32 v69, v127, v128
	v_cvt_pk_bf16_f32 v70, v129, v130
	v_cvt_pk_bf16_f32 v71, v131, v132
	s_nop 0
	v_permlane32_swap_b32_e32 v68, v70
	v_permlane32_swap_b32_e32 v69, v71
	s_waitcnt lgkmcnt(1)
	v_mfma_f32_32x32x16_bf16 v[48:63], v[72:75], v[80:83], v[48:63]
	v_cvt_pk_bf16_f32 v72, v134, v135
	v_cvt_pk_bf16_f32 v73, v136, v137
	v_cvt_pk_bf16_f32 v74, v138, v139
	v_cvt_pk_bf16_f32 v75, v140, v141
	s_nop 0
	v_permlane32_swap_b32_e32 v72, v74
	v_permlane32_swap_b32_e32 v73, v75
	s_waitcnt lgkmcnt(0)
	v_mfma_f32_32x32x16_bf16 v[32:47], v[76:79], v[80:83], v[32:47]
	v_cvt_pk_bf16_f32 v76, v142, v143
	v_cvt_pk_bf16_f32 v77, v152, v153
	v_cvt_pk_bf16_f32 v78, v154, v155
	v_cvt_pk_bf16_f32 v79, v156, v157
	s_nop 0
	v_permlane32_swap_b32_e32 v76, v78
	v_permlane32_swap_b32_e32 v77, v79
	s_or_b32 s0, s1, 1
	s_add_i32 s0, s0, s88
	s_cmp_ge_i32 s0, s3
	s_cselect_b64 s[2:3], -1, 0
	s_cmp_lt_i32 s0, s91
	s_cselect_b64 s[4:5], -1, 0
	s_and_b64 s[2:3], s[2:3], s[4:5]
	v_mov_b32_e32 v179, 0xf149f2ca
	s_andn2_b64 vcc, exec, s[2:3]
	v_mov_b32_e32 v178, 0xf149f2ca
	v_mov_b32_e32 v144, 0xf149f2ca
	v_mov_b32_e32 v115, 0xf149f2ca
	v_mov_b32_e32 v113, 0xf149f2ca
	v_mov_b32_e32 v104, 0xf149f2ca
	v_mov_b32_e32 v102, 0xf149f2ca
	v_mov_b32_e32 v100, 0xf149f2ca
	v_mov_b32_e32 v96, 0xf149f2ca
	v_mov_b32_e32 v94, 0xf149f2ca
	v_mov_b32_e32 v92, 0xf149f2ca
	v_mov_b32_e32 v90, 0xf149f2ca
	v_mov_b32_e32 v88, 0xf149f2ca
	v_mov_b32_e32 v86, 0xf149f2ca
	v_mov_b32_e32 v84, 0xf149f2ca
	v_mov_b32_e32 v82, 0xf149f2ca
	v_mov_b32_e32 v116, 0xf149f2ca
	v_mov_b32_e32 v114, 0xf149f2ca
	v_mov_b32_e32 v105, 0xf149f2ca
	v_mov_b32_e32 v103, 0xf149f2ca
	v_mov_b32_e32 v101, 0xf149f2ca
	v_mov_b32_e32 v97, 0xf149f2ca
	v_mov_b32_e32 v95, 0xf149f2ca
	v_mov_b32_e32 v93, 0xf149f2ca
	v_mov_b32_e32 v91, 0xf149f2ca
	v_mov_b32_e32 v89, 0xf149f2ca
	v_mov_b32_e32 v87, 0xf149f2ca
	v_mov_b32_e32 v85, 0xf149f2ca
	v_mov_b32_e32 v83, 0xf149f2ca
	v_mov_b32_e32 v81, 0xf149f2ca
	v_mov_b32_e32 v80, 0xf149f2ca
	v_mov_b32_e32 v158, 0xf149f2ca
	s_mov_b32 s78, 0x358637bd
	v_readlane_b32 s81, v255, 2
	s_mov_b32 s76, 0xbfb8aa3b
	v_readlane_b32 s37, v255, 28
	v_readlane_b32 s38, v255, 29
	v_readlane_b32 s39, v255, 27
	v_readlane_b32 s40, v255, 26
	s_cbranch_vccnz .LBB0_624
; template <int MODE>
; __device__ __forceinline__ void attn_unit(const UnitArgs& A, char* lds, const int wave_) {
;     ...
;             } else {
;                 const int c = 32 * (qb & 1) + r32; int cs = c - 8; cs = cs < 0 ? 0 : cs; cs = cs > 48 ? 48 : cs;
;                 const float* b = lutB + ((2 * A.h + half) * 15 + (kr - rq + 7)) * 128 + 64 + 4 * hi - c;
; #pragma unroll
;                 for (int r = 0; r < 16; ++r) { const int cc = (r & 3) + 8 * (r >> 2), j = 4 * hi + cc;
;                     p0[r] = ((unsigned)(j - cs) < 16u) ? p0[r] + b[cc] : NEG; p1[r] = ((unsigned)(j + 32 - cs) < 16u) ? p1[r] + b[32 + cc] : NEG; } }
	v_readlane_b32 s1, v255, 32
	s_lshl_b32 s1, s1, 1
	s_add_i32 s1, s41, s1
	s_mul_i32 s1, s1, 15
	s_add_i32 s0, s0, s1
	v_readlane_b32 s1, v255, 33
	s_sub_i32 s0, s0, s1
	s_lshl_b32 s0, s0, 9
	s_add_i32 s0, s0, 0
	s_add_i32 s0, s0, 0x14e00
	v_med3_i32 v98, v112, 8, 56
	v_lshl_add_u32 v80, v107, 4, s0
	v_lshlrev_b32_e32 v81, 2, v112
	v_sub_u32_e32 v99, v80, v81
	v_sub_u32_e32 v80, v108, v98
	v_add_u32_e32 v80, 8, v80
	v_cmp_gt_u32_e32 vcc, 16, v80
	v_mov_b32_e32 v80, 0xf149f2ca
	v_mov_b32_e32 v82, 0xf149f2ca
	ds_read_b32 v246, v99 offset:256
	ds_read_b32 v247, v99 offset:384
	ds_read_b32 v248, v99 offset:260
	ds_read_b32 v249, v99 offset:388
	ds_read_b32 v250, v99 offset:264
	ds_read_b32 v251, v99 offset:392
	ds_read_b32 v252, v99 offset:268
	ds_read_b32 v253, v99 offset:396
	s_waitcnt lgkmcnt(0)
	s_and_saveexec_b64 s[4:5], vcc
	v_add_f32_e32 v82, v48, v246
	s_or_b64 exec, exec, s[4:5]
	v_sub_u32_e32 v48, v176, v98
	v_cmp_gt_u32_e32 vcc, 16, v48
	s_and_saveexec_b64 s[4:5], vcc
	v_add_f32_e32 v80, v32, v247
	s_or_b64 exec, exec, s[4:5]
	v_sub_u32_e32 v32, 8, v98
	v_add3_u32 v48, v32, v108, 1
	v_cmp_gt_u32_e32 vcc, 16, v48
	v_mov_b32_e32 v81, 0xf149f2ca
	v_mov_b32_e32 v84, 0xf149f2ca
	s_and_saveexec_b64 s[4:5], vcc
	v_add_f32_e32 v84, v49, v248
	s_or_b64 exec, exec, s[4:5]
	v_sub_u32_e32 v48, v174, v98
	v_cmp_gt_u32_e32 vcc, 16, v48
	s_and_saveexec_b64 s[4:5], vcc
	v_add_f32_e32 v81, v33, v249
	s_or_b64 exec, exec, s[4:5]
	v_add3_u32 v33, v32, v108, 2
	v_cmp_gt_u32_e32 vcc, 16, v33
	v_mov_b32_e32 v83, 0xf149f2ca
	v_mov_b32_e32 v86, 0xf149f2ca
	s_and_saveexec_b64 s[4:5], vcc
	v_add_f32_e32 v86, v50, v250
	s_or_b64 exec, exec, s[4:5]
	v_sub_u32_e32 v33, v172, v98
	v_cmp_gt_u32_e32 vcc, 16, v33
	s_and_saveexec_b64 s[4:5], vcc
	v_add_f32_e32 v83, v34, v251
	s_or_b64 exec, exec, s[4:5]
	v_add3_u32 v33, v32, v108, 3
	v_cmp_gt_u32_e32 vcc, 16, v33
	v_mov_b32_e32 v85, 0xf149f2ca
	v_mov_b32_e32 v88, 0xf149f2ca
	s_and_saveexec_b64 s[4:5], vcc
	v_add_f32_e32 v88, v51, v252
	s_or_b64 exec, exec, s[4:5]
	v_sub_u32_e32 v33, v171, v98
	v_cmp_gt_u32_e32 vcc, 16, v33
	s_and_saveexec_b64 s[4:5], vcc
	v_add_f32_e32 v85, v35, v253
	s_or_b64 exec, exec, s[4:5]
	v_add3_u32 v33, v32, v108, 8
	v_cmp_gt_u32_e32 vcc, 16, v33
	v_mov_b32_e32 v87, 0xf149f2ca
	v_mov_b32_e32 v90, 0xf149f2ca
	ds_read_b32 v246, v99 offset:288
	ds_read_b32 v247, v99 offset:416
	ds_read_b32 v248, v99 offset:292
	ds_read_b32 v249, v99 offset:420
	ds_read_b32 v250, v99 offset:296
	ds_read_b32 v251, v99 offset:424
	ds_read_b32 v252, v99 offset:300
	ds_read_b32 v253, v99 offset:428
	s_waitcnt lgkmcnt(0)
	s_and_saveexec_b64 s[4:5], vcc
	v_add_f32_e32 v90, v52, v246
	s_or_b64 exec, exec, s[4:5]
	v_sub_u32_e32 v33, v170, v98
	v_cmp_gt_u32_e32 vcc, 16, v33
	s_and_saveexec_b64 s[4:5], vcc
	v_add_f32_e32 v87, v36, v247
	s_or_b64 exec, exec, s[4:5]
	v_add3_u32 v33, v32, v108, 9
	v_cmp_gt_u32_e32 vcc, 16, v33
	v_mov_b32_e32 v89, 0xf149f2ca
	v_mov_b32_e32 v92, 0xf149f2ca
	s_and_saveexec_b64 s[4:5], vcc
	v_add_f32_e32 v92, v53, v248
	s_or_b64 exec, exec, s[4:5]
	v_sub_u32_e32 v33, v169, v98
	v_cmp_gt_u32_e32 vcc, 16, v33
	s_and_saveexec_b64 s[4:5], vcc
	v_add_f32_e32 v89, v37, v249
	s_or_b64 exec, exec, s[4:5]
	v_add3_u32 v33, v32, v108, 10
	v_cmp_gt_u32_e32 vcc, 16, v33
	v_mov_b32_e32 v91, 0xf149f2ca
	v_mov_b32_e32 v94, 0xf149f2ca
	s_and_saveexec_b64 s[4:5], vcc
	v_add_f32_e32 v94, v54, v250
	s_or_b64 exec, exec, s[4:5]
	v_sub_u32_e32 v33, v168, v98
	v_cmp_gt_u32_e32 vcc, 16, v33
	s_and_saveexec_b64 s[4:5], vcc
	v_add_f32_e32 v91, v38, v251
	s_or_b64 exec, exec, s[4:5]
	v_add3_u32 v33, v32, v108, 11
	v_cmp_gt_u32_e32 vcc, 16, v33
	v_mov_b32_e32 v93, 0xf149f2ca
	v_mov_b32_e32 v96, 0xf149f2ca
	s_and_saveexec_b64 s[4:5], vcc
	v_add_f32_e32 v96, v55, v252
	s_or_b64 exec, exec, s[4:5]
	v_sub_u32_e32 v33, v167, v98
	v_cmp_gt_u32_e32 vcc, 16, v33
	s_and_saveexec_b64 s[4:5], vcc
	v_add_f32_e32 v93, v39, v253
	s_or_b64 exec, exec, s[4:5]
	v_add3_u32 v33, v32, v108, 16
	v_cmp_gt_u32_e32 vcc, 16, v33
	v_mov_b32_e32 v95, 0xf149f2ca
	v_mov_b32_e32 v100, 0xf149f2ca
	ds_read_b32 v246, v99 offset:320
	ds_read_b32 v247, v99 offset:448
	ds_read_b32 v248, v99 offset:324
	ds_read_b32 v249, v99 offset:452
	ds_read_b32 v250, v99 offset:328
	ds_read_b32 v251, v99 offset:456
	ds_read_b32 v252, v99 offset:332
	ds_read_b32 v253, v99 offset:460
	s_waitcnt lgkmcnt(0)
; template <int MODE>
; __device__ __forceinline__ void attn_unit(const UnitArgs& A, char* lds, const int wave_) {
;     ...
;             } else {
;                 const int c = 32 * (qb & 1) + r32; int cs = c - 8; cs = cs < 0 ? 0 : cs; cs = cs > 48 ? 48 : cs;
;                 const float* b = lutB + ((2 * A.h + half) * 15 + (kr - rq + 7)) * 128 + 64 + 4 * hi - c;
; #pragma unroll
;                 for (int r = 0; r < 16; ++r) { const int cc = (r & 3) + 8 * (r >> 2), j = 4 * hi + cc;
;                     p0[r] = ((unsigned)(j - cs) < 16u) ? p0[r] + b[cc] : NEG; p1[r] = ((unsigned)(j + 32 - cs) < 16u) ? p1[r] + b[32 + cc] : NEG; } }
	s_and_saveexec_b64 s[4:5], vcc
	v_add_f32_e32 v100, v56, v246
	s_or_b64 exec, exec, s[4:5]
	v_sub_u32_e32 v33, v166, v98
	v_cmp_gt_u32_e32 vcc, 16, v33
	s_and_saveexec_b64 s[4:5], vcc
	v_add_f32_e32 v95, v40, v247
	s_or_b64 exec, exec, s[4:5]
	v_add3_u32 v33, v32, v108, 17
	v_cmp_gt_u32_e32 vcc, 16, v33
	v_mov_b32_e32 v97, 0xf149f2ca
	v_mov_b32_e32 v102, 0xf149f2ca
	s_and_saveexec_b64 s[4:5], vcc
	v_add_f32_e32 v102, v57, v248
	s_or_b64 exec, exec, s[4:5]
	v_sub_u32_e32 v33, v165, v98
	v_cmp_gt_u32_e32 vcc, 16, v33
	s_and_saveexec_b64 s[4:5], vcc
	v_add_f32_e32 v97, v41, v249
	s_or_b64 exec, exec, s[4:5]
	v_add3_u32 v33, v32, v108, 18
	v_cmp_gt_u32_e32 vcc, 16, v33
	v_mov_b32_e32 v101, 0xf149f2ca
	v_mov_b32_e32 v104, 0xf149f2ca
	s_and_saveexec_b64 s[4:5], vcc
	v_add_f32_e32 v104, v58, v250
	s_or_b64 exec, exec, s[4:5]
	v_sub_u32_e32 v33, v164, v98
	v_cmp_gt_u32_e32 vcc, 16, v33
	s_and_saveexec_b64 s[4:5], vcc
	v_add_f32_e32 v101, v42, v251
	s_or_b64 exec, exec, s[4:5]
	v_add3_u32 v33, v32, v108, 19
	v_cmp_gt_u32_e32 vcc, 16, v33
	v_mov_b32_e32 v103, 0xf149f2ca
	v_mov_b32_e32 v113, 0xf149f2ca
	s_and_saveexec_b64 s[4:5], vcc
	v_add_f32_e32 v113, v59, v252
	s_or_b64 exec, exec, s[4:5]
	v_sub_u32_e32 v33, v163, v98
	v_cmp_gt_u32_e32 vcc, 16, v33
	s_and_saveexec_b64 s[4:5], vcc
	v_add_f32_e32 v103, v43, v253
	s_or_b64 exec, exec, s[4:5]
	v_add3_u32 v33, v32, v108, 24
	v_cmp_gt_u32_e32 vcc, 16, v33
	v_mov_b32_e32 v105, 0xf149f2ca
	v_mov_b32_e32 v115, 0xf149f2ca
	ds_read_b32 v246, v99 offset:352
	ds_read_b32 v247, v99 offset:480
	ds_read_b32 v248, v99 offset:356
	ds_read_b32 v249, v99 offset:484
	ds_read_b32 v250, v99 offset:360
	ds_read_b32 v251, v99 offset:488
	ds_read_b32 v252, v99 offset:364
	ds_read_b32 v253, v99 offset:492
	s_waitcnt lgkmcnt(0)
	s_and_saveexec_b64 s[4:5], vcc
	v_add_f32_e32 v115, v60, v246
	s_or_b64 exec, exec, s[4:5]
	v_sub_u32_e32 v33, v162, v98
	v_cmp_gt_u32_e32 vcc, 16, v33
	s_and_saveexec_b64 s[4:5], vcc
	v_add_f32_e32 v105, v44, v247
	s_or_b64 exec, exec, s[4:5]
	v_add3_u32 v33, v32, v108, 25
	v_cmp_gt_u32_e32 vcc, 16, v33
	v_mov_b32_e32 v114, 0xf149f2ca
	v_mov_b32_e32 v144, 0xf149f2ca
	s_and_saveexec_b64 s[4:5], vcc
	v_add_f32_e32 v144, v61, v248
	s_or_b64 exec, exec, s[4:5]
	v_sub_u32_e32 v33, v160, v98
	v_cmp_gt_u32_e32 vcc, 16, v33
	s_and_saveexec_b64 s[4:5], vcc
	v_add_f32_e32 v114, v45, v249
	s_or_b64 exec, exec, s[4:5]
	v_add3_u32 v33, v32, v108, 26
	v_cmp_gt_u32_e32 vcc, 16, v33
	v_mov_b32_e32 v116, 0xf149f2ca
	v_mov_b32_e32 v178, 0xf149f2ca
	s_and_saveexec_b64 s[4:5], vcc
	v_add_f32_e32 v178, v62, v250
	s_or_b64 exec, exec, s[4:5]
	v_sub_u32_e32 v33, v159, v98
	v_cmp_gt_u32_e32 vcc, 16, v33
	s_and_saveexec_b64 s[4:5], vcc
	v_add_f32_e32 v116, v46, v251
	s_or_b64 exec, exec, s[4:5]
	v_add3_u32 v32, v32, v108, 27
	v_cmp_gt_u32_e32 vcc, 16, v32
	v_mov_b32_e32 v158, 0xf149f2ca
	v_mov_b32_e32 v179, 0xf149f2ca
	s_and_saveexec_b64 s[4:5], vcc
	v_add_f32_e32 v179, v63, v252
	s_or_b64 exec, exec, s[4:5]
	v_sub_u32_e32 v32, v133, v98
	v_cmp_gt_u32_e32 vcc, 16, v32
	s_and_saveexec_b64 s[4:5], vcc
	v_add_f32_e32 v158, v47, v253
	s_or_b64 exec, exec, s[4:5]
